# on top of flat release poll: forgetting-attention pipelined step reads the decay image and the second K tile through offset immediates from persistent base registers (19 address VALU ops fewer per ste
# speedup vs baseline: 1.0018x; 1.0018x over previous
.LBB0_887:
	s_andn2_b64 vcc, exec, s[4:5]
	s_cbranch_vccnz .LBB0_889
	v_add_u32_e32 v246, s33, v202
	v_add_u32_e32 v246, 0x18a00, v246
	s_nop 6
	v_add_u32_e32 v0, s58, v197
	v_add_u32_e32 v247, s58, v195
	ds_read_b128 v[66:69], v247
	ds_read_b128 v[70:73], v247 offset:4096
	v_add_u32_e32 v248, s58, v198
	ds_read_b128 v[74:77], v248
	ds_read_b128 v[78:81], v248 offset:4096
	v_add_u32_e32 v249, s58, v199
	ds_read_b128 v[82:85], v249
	ds_read_b128 v[86:89], v249 offset:4096
	v_add_u32_e32 v250, s58, v200
	ds_read_b128 v[90:93], v250
	ds_read_b128 v[94:97], v250 offset:4096
	ds_read_b128 v[34:37], v246 offset:256
	ds_read_b128 v[50:53], v246 offset:384
	ds_read_b128 v[38:41], v246 offset:288
	ds_read_b128 v[54:57], v246 offset:416
	ds_read_b128 v[42:45], v246 offset:320
	ds_read_b128 v[58:61], v246 offset:448
	ds_read_b128 v[46:49], v246 offset:352
	ds_read_b128 v[62:65], v246 offset:480
	s_waitcnt lgkmcnt(1)
	v_mfma_f32_32x32x16_bf16 v[34:49], v[66:69], v[146:149], v[34:49]
	s_waitcnt lgkmcnt(0)
	v_mfma_f32_32x32x16_bf16 v[50:65], v[70:73], v[146:149], v[50:65]
	v_mfma_f32_32x32x16_bf16 v[34:49], v[74:77], v[150:153], v[34:49]
	v_mfma_f32_32x32x16_bf16 v[50:65], v[78:81], v[150:153], v[50:65]
	v_mfma_f32_32x32x16_bf16 v[34:49], v[82:85], v[154:157], v[34:49]
	v_mfma_f32_32x32x16_bf16 v[50:65], v[86:89], v[154:157], v[50:65]
	v_mfma_f32_32x32x16_bf16 v[34:49], v[90:93], v[158:161], v[34:49]
	v_mfma_f32_32x32x16_bf16 v[50:65], v[94:97], v[158:161], v[50:65]
	s_add_i32 s4, s58, 0x2000
	ds_read_b128 v[82:85], v247 offset:8192
	ds_read_b128 v[66:69], v246
	ds_read_b128 v[70:73], v246 offset:32
	ds_read_b128 v[74:77], v246 offset:64
	ds_read_b128 v[78:81], v246 offset:96
	s_nop 5
	v_exp_f32_e32 v162, v50
	v_exp_f32_e32 v138, v51
	v_exp_f32_e32 v130, v52
	s_waitcnt lgkmcnt(0)
	v_mfma_f32_32x32x16_bf16 v[66:81], v[82:85], v[146:149], v[66:81]
	ds_read_b128 v[82:85], v248 offset:8192
	ds_read_b128 v[86:89], v250 offset:8192
	v_exp_f32_e32 v122, v34
	v_exp_f32_e32 v134, v35
	v_exp_f32_e32 v126, v36
	v_exp_f32_e32 v116, v37
	s_waitcnt lgkmcnt(1)
	v_mfma_f32_32x32x16_bf16 v[66:81], v[82:85], v[150:153], v[66:81]
	ds_read_b128 v[82:85], v249 offset:8192
	ds_read_b128 v[34:37], v247 offset:12288
	ds_read_b128 v[90:93], v246 offset:192
	ds_read_b128 v[94:97], v246 offset:224
	v_exp_f32_e32 v172, v53
	v_exp_f32_e32 v186, v38
	v_exp_f32_e32 v168, v39
	s_waitcnt lgkmcnt(3)
	v_mfma_f32_32x32x16_bf16 v[66:81], v[82:85], v[154:157], v[66:81]
	ds_read_b128 v[82:85], v246 offset:128
	v_exp_f32_e32 v164, v40
	v_exp_f32_e32 v142, v41
	ds_read_b128 v[38:41], v250 offset:12288
	v_exp_f32_e32 v244, v54
	v_exp_f32_e32 v170, v55
	v_exp_f32_e32 v166, v56
	v_mfma_f32_32x32x16_bf16 v[66:81], v[86:89], v[158:161], v[66:81]
	ds_read_b128 v[86:89], v246 offset:160
	ds_read_b128 v[50:53], v248 offset:12288
	v_exp_f32_e32 v144, v57
	v_exp_f32_e32 v136, v42
	v_exp_f32_e32 v140, v58
	v_exp_f32_e32 v128, v43
	v_exp_f32_e32 v132, v59
	s_waitcnt lgkmcnt(1)
	v_mfma_f32_32x32x16_bf16 v[82:97], v[34:37], v[146:149], v[82:97]
	ds_read_b128 v[34:37], v249 offset:12288
	v_exp_f32_e32 v120, v44
	v_exp_f32_e32 v124, v60
	v_exp_f32_e32 v114, v45
	v_exp_f32_e32 v118, v61
	v_exp_f32_e32 v110, v46
	v_exp_f32_e32 v112, v62
	s_waitcnt lgkmcnt(1)
	v_mfma_f32_32x32x16_bf16 v[82:97], v[50:53], v[150:153], v[82:97]
	v_exp_f32_e32 v104, v47
	v_exp_f32_e32 v108, v63
	v_exp_f32_e32 v102, v48
	v_exp_f32_e32 v98, v49
	v_exp_f32_e32 v106, v64
	v_exp_f32_e32 v100, v65
	s_waitcnt lgkmcnt(0)
	v_mfma_f32_32x32x16_bf16 v[82:97], v[34:37], v[154:157], v[82:97]
	v_mfma_f32_32x32x16_bf16 v[82:97], v[38:41], v[158:161], v[82:97]
	v_cvt_pk_bf16_f32 v213, v126, v116
	v_cvt_pk_bf16_f32 v214, v186, v168
	v_cvt_pk_bf16_f32 v215, v164, v142
	v_cvt_pk_bf16_f32 v174, v136, v128
	v_cvt_pk_bf16_f32 v175, v120, v114
	v_cvt_pk_bf16_f32 v176, v110, v104
	v_cvt_pk_bf16_f32 v177, v102, v98
	v_cvt_pk_bf16_f32 v178, v162, v138
	v_cvt_pk_bf16_f32 v179, v130, v172
	v_cvt_pk_bf16_f32 v180, v244, v170
	v_cvt_pk_bf16_f32 v181, v166, v144
	v_cvt_pk_bf16_f32 v208, v140, v132
	v_cvt_pk_bf16_f32 v209, v124, v118
	v_cvt_pk_bf16_f32 v210, v112, v108
	v_cvt_pk_bf16_f32 v211, v106, v100
	v_cvt_pk_bf16_f32 v212, v122, v134
	ds_read_b64_tr_b16 v[50:51], v0 offset:16384
	ds_read_b64_tr_b16 v[52:53], v0 offset:16896
	ds_read_b64_tr_b16 v[216:217], v0 offset:20480
	ds_read_b64_tr_b16 v[218:219], v0 offset:20992
	v_exp_f32_e32 v123, v66
	v_exp_f32_e32 v163, v82
	v_exp_f32_e32 v135, v67
	v_exp_f32_e32 v139, v83
	v_exp_f32_e32 v127, v68
	v_exp_f32_e32 v187, v70
	v_exp_f32_e32 v245, v86
	v_exp_f32_e32 v131, v84
	v_exp_f32_e32 v117, v69
	v_exp_f32_e32 v173, v85
	v_exp_f32_e32 v169, v71
	v_exp_f32_e32 v165, v72
	v_exp_f32_e32 v143, v73
	v_exp_f32_e32 v137, v74
	v_exp_f32_e32 v129, v75
	v_exp_f32_e32 v121, v76
	v_exp_f32_e32 v115, v77
	v_exp_f32_e32 v111, v78
	v_exp_f32_e32 v105, v79
	v_exp_f32_e32 v103, v80
	v_exp_f32_e32 v99, v81
	ds_read_b64_tr_b16 v[220:221], v0 offset:17408
	ds_read_b64_tr_b16 v[222:223], v0 offset:17920
	ds_read_b64_tr_b16 v[224:225], v0 offset:21504
	ds_read_b64_tr_b16 v[226:227], v0 offset:22016
	ds_read_b64_tr_b16 v[228:229], v0 offset:18432
	ds_read_b64_tr_b16 v[230:231], v0 offset:18944
	ds_read_b64_tr_b16 v[232:233], v0 offset:22528
	ds_read_b64_tr_b16 v[234:235], v0 offset:23040
	ds_read_b64_tr_b16 v[236:237], v0 offset:19456
	ds_read_b64_tr_b16 v[238:239], v0 offset:19968
	ds_read_b64_tr_b16 v[240:241], v0 offset:23552
	ds_read_b64_tr_b16 v[242:243], v0 offset:24064
	s_waitcnt lgkmcnt(14)
	v_mfma_f32_32x32x16_bf16 v[34:49], v[212:215], v[50:53], v[18:33]
	v_add_f32_e64 v66, v186, v244
	v_add_f32_e64 v67, v187, v245
	v_cvt_pk_bf16_f32 v68, v123, v135
	v_cvt_pk_bf16_f32 v69, v127, v117
	v_cvt_pk_bf16_f32 v70, v187, v169
	v_cvt_pk_bf16_f32 v71, v165, v143
	v_cvt_pk_bf16_f32 v72, v137, v129
	v_cvt_pk_bf16_f32 v73, v121, v115
	v_cvt_pk_bf16_f32 v74, v111, v105
	v_cvt_pk_bf16_f32 v75, v103, v99
	v_cvt_pk_bf16_f32 v76, v163, v139
	v_cvt_pk_bf16_f32 v77, v131, v173
	s_waitcnt lgkmcnt(12)
	v_mfma_f32_32x32x16_bf16 v[50:65], v[212:215], v[216:219], v[2:17]
	v_exp_f32_e32 v171, v87
	v_exp_f32_e32 v167, v88
	v_exp_f32_e32 v145, v89
	v_exp_f32_e32 v141, v90
	v_exp_f32_e32 v133, v91
	v_exp_f32_e32 v125, v92
	v_exp_f32_e32 v119, v93
	v_exp_f32_e32 v113, v94
	v_exp_f32_e32 v109, v95
	v_exp_f32_e32 v107, v96
	v_exp_f32_e32 v101, v97
	v_cvt_pk_bf16_f32 v78, v245, v171
	v_cvt_pk_bf16_f32 v79, v167, v145
	v_cvt_pk_bf16_f32 v80, v141, v133
	v_cvt_pk_bf16_f32 v81, v125, v119
	v_cvt_pk_bf16_f32 v82, v113, v109
	v_cvt_pk_bf16_f32 v83, v107, v101
	s_waitcnt lgkmcnt(10)
	v_mfma_f32_32x32x16_bf16 v[34:49], v[174:177], v[220:223], v[34:49]
	v_add_f32_e64 v84, v122, v162
	v_add_f32_e64 v85, v123, v163
	v_add_f32_e64 v86, v134, v138
	v_add_f32_e64 v87, v135, v139
	v_add_f32_e64 v84, v84, 0
	v_add_f32_e64 v85, v85, 0
	v_pk_add_f32 v[88:89], v[126:127], v[130:131]
	v_pk_add_f32 v[84:85], v[86:87], v[84:85]
	v_pk_add_f32 v[90:91], v[116:117], v[172:173]
	v_pk_add_f32 v[84:85], v[88:89], v[84:85]
	s_waitcnt lgkmcnt(8)
	v_mfma_f32_32x32x16_bf16 v[50:65], v[174:177], v[224:227], v[50:65]
	v_add_f32_e64 v84, v90, v84
	v_add_f32_e64 v85, v91, v85
	v_add_f32_e64 v86, v168, v170
	v_add_f32_e64 v87, v169, v171
	v_add_f32_e64 v66, v66, v84
	v_add_f32_e64 v67, v67, v85
	v_pk_add_f32 v[88:89], v[164:165], v[166:167]
	v_pk_add_f32 v[66:67], v[86:87], v[66:67]
	v_pk_add_f32 v[90:91], v[142:143], v[144:145]
	v_pk_add_f32 v[66:67], v[88:89], v[66:67]
	s_waitcnt lgkmcnt(6)
	v_mfma_f32_32x32x16_bf16 v[34:49], v[178:181], v[228:231], v[34:49]
	v_add_f32_e64 v92, v136, v140
	v_add_f32_e64 v93, v137, v141
	v_add_f32_e64 v66, v90, v66
	v_add_f32_e64 v67, v91, v67
	v_add_f32_e64 v94, v128, v132
	v_add_f32_e64 v95, v129, v133
	v_pk_add_f32 v[66:67], v[92:93], v[66:67]
	v_pk_add_f32 v[96:97], v[120:121], v[124:125]
	v_pk_add_f32 v[66:67], v[94:95], v[66:67]
	v_pk_add_f32 v[114:115], v[114:115], v[118:119]
	s_waitcnt lgkmcnt(4)
	v_mfma_f32_32x32x16_bf16 v[50:65], v[178:181], v[232:235], v[50:65]
	v_add_f32_e64 v66, v96, v66
	v_add_f32_e64 v67, v97, v67
	v_add_f32_e64 v110, v110, v112
	v_add_f32_e64 v111, v111, v113
	v_add_f32_e64 v66, v114, v66
	v_add_f32_e64 v67, v115, v67
	v_pk_add_f32 v[104:105], v[104:105], v[108:109]
	v_pk_add_f32 v[66:67], v[110:111], v[66:67]
	v_pk_add_f32 v[102:103], v[102:103], v[106:107]
	v_pk_add_f32 v[66:67], v[104:105], v[66:67]
	s_waitcnt lgkmcnt(2)
	v_mfma_f32_32x32x16_bf16 v[34:49], v[208:211], v[236:239], v[34:49]
	v_add_f32_e64 v98, v98, v100
	v_add_f32_e64 v99, v99, v101
	v_add_f32_e64 v66, v102, v66
	v_add_f32_e64 v67, v103, v67
	v_add_f32_e64 v66, v98, v66
	v_add_f32_e64 v67, v99, v67
	v_add_f32_e32 v66, v205, v66
	s_waitcnt lgkmcnt(0)
	v_mfma_f32_32x32x16_bf16 v[50:65], v[208:211], v[240:243], v[50:65]
	v_add_f32_e32 v66, v66, v67
	ds_read_b64_tr_b16 v[84:85], v0 offset:24576
	ds_read_b64_tr_b16 v[86:87], v0 offset:25088
	ds_read_b64_tr_b16 v[88:89], v0 offset:25600
	ds_read_b64_tr_b16 v[90:91], v0 offset:26112
	s_waitcnt lgkmcnt(2)
	v_mfma_f32_32x32x16_bf16 v[34:49], v[68:71], v[84:87], v[34:49]
	ds_read_b64_tr_b16 v[84:85], v0 offset:28672
	ds_read_b64_tr_b16 v[86:87], v0 offset:29184
	ds_read_b64_tr_b16 v[92:93], v0 offset:29696
	ds_read_b64_tr_b16 v[94:95], v0 offset:30208
	s_waitcnt lgkmcnt(2)
	v_mfma_f32_32x32x16_bf16 v[50:65], v[68:71], v[84:87], v[50:65]
	ds_read_b64_tr_b16 v[68:69], v0 offset:26624
	ds_read_b64_tr_b16 v[70:71], v0 offset:27136
	ds_read_b64_tr_b16 v[84:85], v0 offset:31744
	ds_read_b64_tr_b16 v[86:87], v0 offset:32256
	v_mfma_f32_32x32x16_bf16 v[34:49], v[72:75], v[88:91], v[34:49]
	s_waitcnt lgkmcnt(4)
	v_mfma_f32_32x32x16_bf16 v[50:65], v[72:75], v[92:95], v[50:65]
	ds_read_b64_tr_b16 v[72:73], v0 offset:27648
	ds_read_b64_tr_b16 v[74:75], v0 offset:28160
	s_waitcnt lgkmcnt(4)
	v_mfma_f32_32x32x16_bf16 v[34:49], v[76:79], v[68:71], v[34:49]
	ds_read_b64_tr_b16 v[68:69], v0 offset:30720
	ds_read_b64_tr_b16 v[70:71], v0 offset:31232
	s_waitcnt lgkmcnt(0)
	v_mfma_f32_32x32x16_bf16 v[50:65], v[76:79], v[68:71], v[50:65]
	v_mfma_f32_32x32x16_bf16 v[34:49], v[80:83], v[72:75], v[34:49]
	v_mfma_f32_32x32x16_bf16 v[50:65], v[80:83], v[84:87], v[50:65]
